# GEMM phase prologues de-serialised: all 14 first-tile DMA pieces issued before the single counted wait
# speedup vs baseline: 1.0019x; 1.0019x over previous
.LBB0_127:
	s_lshl_b32 s6, s6, 5
	s_and_b32 s13, s6, 0x60
	s_lshl_b32 s12, s5, 13
	s_lshl_b32 s14, s13, 7
	s_add_u32 s6, s33, 0x9800000
	s_mov_b64 s[8:9], 0x80
	s_addc_u32 s7, s34, 0
	s_add_i32 m0, s19, 0x18000
	v_lshl_add_u64 v[6:7], v[6:7], 0, s[8:9]
	s_nop 0
	s_barrier
	global_load_lds_dwordx4 v[6:7], off
	v_lshl_add_u64 v[4:5], v[4:5], 0, s[8:9]
	s_add_i32 m0, s19, 0x1a000
	s_add_i32 s45, s19, 0x8000
	s_add_i32 s46, s19, 0xa000
	global_load_lds_dwordx4 v[4:5], off
	v_lshl_add_u64 v[2:3], v[2:3], 0, s[8:9]
	s_mov_b32 m0, s45
	s_add_u32 s10, s26, 0x40080
	global_load_lds_dwordx4 v[2:3], off
	v_lshl_add_u64 v[0:1], v[0:1], 0, s[8:9]
	s_mov_b32 m0, s46
	s_addc_u32 s11, s27, 0
	global_load_lds_dwordx4 v[0:1], off
	s_add_i32 m0, s19, 0x1c000
	v_lshl_add_u64 v[0:1], s[10:11], 0, v[132:133]
	global_load_lds_dwordx4 v[0:1], off
	v_lshl_add_u64 v[0:1], s[10:11], 0, v[128:129]
	s_add_i32 m0, s19, 0x1e000
	s_sext_i32_i16 s52, s4
	global_load_lds_dwordx4 v[0:1], off
	v_lshrrev_b32_e32 v1, 1, v146
	v_and_b32_e32 v1, 24, v1
	s_lshl_b32 s4, s5, 8
	v_and_b32_e32 v0, 15, v146
	v_lshlrev_b32_e32 v2, 1, v1
	s_add_i32 s4, s4, 0
	v_lshl_or_b32 v144, s5, 6, v0
	v_lshl_or_b32 v2, v0, 6, v2
	v_lshlrev_b32_e32 v0, 2, v0
	s_add_i32 s4, s4, 0x20000
	v_and_b32_e32 v3, 32, v0
	v_add_u32_e32 v147, s4, v0
	v_lshlrev_b32_e32 v0, 14, v12
	v_and_b32_e32 v0, 0xffff8000, v0
	v_or_b32_e32 v148, s13, v1
	v_lshl_add_u32 v0, v11, 11, v0
	v_and_b32_e32 v1, 1, v12
	v_lshl_or_b32 v0, v1, 6, v0
	v_lshl_add_u32 v136, v13, 1, v0
	v_lshlrev_b32_e32 v0, 14, v8
	v_and_b32_e32 v0, 0xffff8000, v0
	s_waitcnt vmcnt(6)
	v_lshl_add_u32 v0, v9, 11, v0
	v_and_b32_e32 v1, 1, v8
	v_bitop3_b32 v4, v2, s12, v3 bitop3:0xde
	v_bitop3_b32 v145, s14, v2, v3 bitop3:0xf6
	v_lshl_or_b32 v0, v1, 6, v0
	s_add_i32 s47, 0, 0x10000
	s_add_i32 s48, 0, 0x14000
	v_mov_b32_e32 v137, v133
	v_lshl_add_u32 v138, v10, 1, v0
	v_mov_b32_e32 v139, v133
	v_mov_b64_e32 v[140:141], 0x1080
	v_mov_b64_e32 v[142:143], 0x107f
	v_add_u32_e32 v149, s47, v145
	v_add_u32_e32 v150, 0, v4
	v_add_u32_e32 v151, s48, v145
	s_movk_i32 s49, 0x1600
	s_barrier

.LBB0_239:
	s_add_u32 s14, s6, 0x3800000
	s_addc_u32 s15, s7, 0
	s_add_u32 s16, s6, 0x2d00000
	s_mov_b64 s[18:19], 0x80
	s_addc_u32 s17, s7, 0
	s_and_b32 s45, s4, 3
	s_add_i32 m0, s41, 0x18000
	v_lshl_add_u64 v[6:7], v[6:7], 0, s[18:19]
	s_lshl_b32 s4, s5, 13
	s_lshl_b32 s9, s45, 12
	s_nop 0
	s_barrier
	global_load_lds_dwordx4 v[6:7], off
	v_lshl_add_u64 v[4:5], v[4:5], 0, s[18:19]
	s_add_i32 m0, s41, 0x1a000
	s_add_i32 s46, s41, 0x8000
	s_add_i32 s47, s41, 0xa000
	global_load_lds_dwordx4 v[4:5], off
	v_lshl_add_u64 v[2:3], v[2:3], 0, s[18:19]
	s_mov_b32 m0, s46
	s_add_u32 s6, s26, 0xb0080
	global_load_lds_dwordx4 v[2:3], off
	v_lshl_add_u64 v[0:1], v[0:1], 0, s[18:19]
	s_mov_b32 m0, s47
	s_addc_u32 s7, s27, 0
	global_load_lds_dwordx4 v[0:1], off
	s_add_i32 m0, s41, 0x1c000
	v_lshl_add_u64 v[0:1], s[6:7], 0, v[130:131]
	global_load_lds_dwordx4 v[0:1], off
	v_lshl_add_u64 v[0:1], s[6:7], 0, v[134:135]
	s_add_i32 m0, s41, 0x1e000
	s_mov_b64 s[6:7], 0xb0080
	global_load_lds_dwordx4 v[0:1], off
	v_bfe_u32 v0, v8, 4, 2
	v_and_b32_e32 v1, 15, v8
	v_lshlrev_b32_e32 v3, 4, v0
	v_lshl_or_b32 v148, s5, 6, v1
	v_lshl_or_b32 v1, v1, 6, v3
	v_lshlrev_b32_e32 v3, 2, v8
	v_and_b32_e32 v3, 32, v3
	v_lshlrev_b32_e32 v2, 3, v0
	v_bitop3_b32 v4, v1, s4, v3 bitop3:0xde
	v_bitop3_b32 v149, s9, v1, v3 bitop3:0xf6
	v_cmp_eq_u32_e64 s[4:5], 0, v0
	v_lshrrev_b32_e32 v1, 1, v9
	v_mul_lo_u32 v0, v11, s8
	s_mov_b32 s9, 0xb000
	v_mad_u64_u32 v[0:1], s[10:11], v1, s9, v[0:1]
	v_or_b32_e32 v0, v0, v10
	v_add_lshl_u32 v0, v0, v12, 1
	v_mov_b32_e32 v1, v131
	v_lshl_add_u64 v[136:137], v[0:1], 0, s[6:7]
	v_lshrrev_b32_e32 v1, 1, v13
	v_mul_lo_u32 v0, v14, s8
	v_mad_u64_u32 v[0:1], s[8:9], v1, s9, v[0:1]
	s_waitcnt vmcnt(6)
	v_or_b32_e32 v0, v0, v15
	v_add_lshl_u32 v0, v0, v16, 1
	v_mov_b32_e32 v1, v131
	s_add_i32 s51, 0, 0x10000
	s_add_i32 s52, 0, 0x14000
	v_lshl_or_b32 v150, s45, 5, v2
	s_ashr_i32 s48, s34, 31
	s_ashr_i32 s49, s33, 31
	v_lshl_add_u64 v[138:139], v[0:1], 0, s[6:7]
	v_mov_b64_e32 v[140:141], 0x300
	v_mov_b64_e32 v[142:143], 0x2ff
	s_movk_i32 s50, 0x61
	v_add_u32_e32 v151, s51, v149
	v_add_u32_e32 v152, 0, v4
	v_add_u32_e32 v153, s52, v149
	v_mbcnt_hi_u32_b32 v154, -1, v241
	s_mov_b32 s53, 0
	s_barrier
	s_branch .LBB0_241

.LBB0_353:
	s_mov_b64 s[10:11], 0x80
	s_and_b32 s4, s4, 3
	s_add_i32 m0, s37, 0x18000
	v_lshl_add_u64 v[6:7], v[6:7], 0, s[10:11]
	s_lshl_b32 s14, s5, 13
	s_lshl_b32 s18, s4, 5
	s_lshl_b32 s15, s4, 12
	s_nop 0
	s_barrier
	global_load_lds_dwordx4 v[6:7], off
	v_lshl_add_u64 v[4:5], v[4:5], 0, s[10:11]
	s_add_i32 m0, s37, 0x1a000
	s_add_i32 s55, s37, 0x8000
	s_add_i32 s56, s37, 0xa000
	global_load_lds_dwordx4 v[4:5], off
	v_lshl_add_u64 v[2:3], v[2:3], 0, s[10:11]
	s_mov_b32 m0, s55
	s_add_u32 s12, s38, 0x40080
	global_load_lds_dwordx4 v[2:3], off
	v_lshl_add_u64 v[0:1], v[0:1], 0, s[10:11]
	s_mov_b32 m0, s56
	s_addc_u32 s13, s39, 0
	global_load_lds_dwordx4 v[0:1], off
	s_add_i32 m0, s37, 0x1c000
	v_lshl_add_u64 v[0:1], s[12:13], 0, v[144:145]
	global_load_lds_dwordx4 v[0:1], off
	v_lshl_add_u64 v[0:1], s[12:13], 0, v[148:149]
	s_add_i32 m0, s37, 0x1e000
	v_mov_b32_e32 v159, v151
	global_load_lds_dwordx4 v[0:1], off
	v_and_b32_e32 v0, 15, v153
	v_lshl_or_b32 v178, s5, 6, v0
	v_lshrrev_b32_e32 v1, 1, v153
	s_lshl_b32 s5, s5, 8
	v_and_b32_e32 v152, 24, v1
	s_add_i32 s5, s5, 0
	v_lshlrev_b32_e32 v1, 1, v152
	s_add_i32 s5, s5, 0x20000
	v_lshl_or_b32 v1, v0, 6, v1
	v_lshlrev_b32_e32 v0, 2, v0
	s_add_u32 s12, s26, 0xf800000
	v_and_b32_e32 v2, 32, v0
	s_addc_u32 s13, s27, 0
	v_bitop3_b32 v3, v1, s14, v2 bitop3:0xde
	s_add_u32 s14, s26, 0xe000000
	v_bitop3_b32 v179, s15, v1, v2 bitop3:0xf6
	s_addc_u32 s15, s27, 0
	s_cmp_lt_u32 s4, 2
	s_cselect_b64 s[16:17], -1, 0
	s_lshl_b32 s57, s4, 6
	s_lshl_b32 s4, s4, 7
	s_add_u32 s4, s26, s4
	v_add_u32_e32 v180, s5, v0
	s_addc_u32 s5, s27, 0
	s_add_u32 s19, s4, 0xd3fff00
	s_addc_u32 s20, s5, 0
	s_add_u32 s21, s4, 0xc800000
	v_lshlrev_b32_e32 v150, 2, v152
	s_addc_u32 s30, s5, 0
	v_lshl_add_u64 v[0:1], s[26:27], 0, v[150:151]
	s_mov_b64 s[4:5], 0x2800000
	v_lshl_add_u64 v[154:155], v[0:1], 0, s[4:5]
	s_mov_b64 s[4:5], 0x2900000
	v_lshl_add_u64 v[156:157], v[0:1], 0, s[4:5]
	v_lshlrev_b32_e32 v0, 14, v8
	v_and_b32_e32 v0, 0xffff8000, v0
	v_lshl_add_u32 v0, v9, 11, v0
	v_and_b32_e32 v1, 1, v8
	v_lshl_or_b32 v0, v1, 6, v0
	s_add_u32 s58, s26, 0x9800000
	v_lshl_add_u32 v158, v10, 1, v0
	v_lshlrev_b32_e32 v0, 14, v11
	s_addc_u32 s59, s27, 0
	v_and_b32_e32 v0, 0xffff8000, v0
	s_waitcnt vmcnt(6)
	s_and_b64 s[4:5], s[16:17], exec
	v_lshl_add_u32 v0, v12, 11, v0
	v_and_b32_e32 v1, 1, v11
	s_cselect_b32 s60, s30, s20
	s_cselect_b32 s61, s21, s19
	v_lshl_or_b32 v0, v1, 6, v0
	s_add_i32 s63, 0, 0x10000
	s_add_i32 s64, 0, 0x14000
	v_lshl_add_u32 v160, v13, 1, v0
	v_mov_b32_e32 v161, v151
	v_mov_b64_e32 v[162:163], 0x6c0
	v_mov_b64_e32 v[164:165], 0x6bf
	s_movk_i32 s62, 0xd9
	v_add_u32_e32 v181, s63, v179
	v_add_u32_e32 v182, 0, v3
	v_add_u32_e32 v183, s64, v179
	s_lshl_b32 s65, s18, 1
	s_movk_i32 s66, 0x3f80
	s_movk_i32 s67, 0x3f70
	s_movk_i32 s68, 0x3f60
	s_movk_i32 s69, 0x3f50
	v_mov_b32_e32 v184, 0x1fcf
	v_mov_b32_e32 v185, 0x7cf
	v_mov_b32_e32 v186, 0x1fdf
	v_mov_b32_e32 v187, 0x7df
	v_mov_b32_e32 v188, 0x1fef
	v_mov_b32_e32 v189, 0x7ef
	v_mov_b32_e32 v190, 0x1fff
	v_mov_b32_e32 v191, 0x7ff
	s_barrier
	s_branch .LBB0_356

.LBB0_781:
	s_add_u32 s10, s6, 0x3800000
	s_addc_u32 s11, s7, 0
	s_add_u32 s12, s6, 0x3000000
	s_addc_u32 s13, s7, 0
	s_and_b32 s49, s14, 3
	s_mov_b64 s[14:15], 0x80
	s_add_i32 m0, s45, 0x18000
	v_lshl_add_u64 v[6:7], v[6:7], 0, s[14:15]
	s_lshl_b32 s16, s5, 13
	s_lshl_b32 s17, s49, 12
	s_nop 0
	s_barrier
	global_load_lds_dwordx4 v[6:7], off
	v_lshl_add_u64 v[4:5], v[4:5], 0, s[14:15]
	s_add_i32 m0, s45, 0x1a000
	s_add_i32 s50, s45, 0x8000
	s_add_i32 s51, s45, 0xa000
	global_load_lds_dwordx4 v[4:5], off
	v_lshl_add_u64 v[2:3], v[2:3], 0, s[14:15]
	s_mov_b32 m0, s50
	s_add_u32 s6, s30, 0x40080
	global_load_lds_dwordx4 v[2:3], off
	v_lshl_add_u64 v[0:1], v[0:1], 0, s[14:15]
	s_mov_b32 m0, s51
	s_addc_u32 s7, s31, 0
	global_load_lds_dwordx4 v[0:1], off
	s_add_i32 m0, s45, 0x1c000
	v_lshl_add_u64 v[0:1], s[6:7], 0, v[132:133]
	global_load_lds_dwordx4 v[0:1], off
	v_lshl_add_u64 v[0:1], s[6:7], 0, v[128:129]
	s_add_i32 m0, s45, 0x1e000
	s_sext_i32_i8 s56, s4
	global_load_lds_dwordx4 v[0:1], off
	v_bfe_u32 v0, v8, 4, 2
	v_and_b32_e32 v1, 15, v8
	v_lshlrev_b32_e32 v3, 4, v0
	v_lshl_or_b32 v148, s5, 6, v1
	v_lshlrev_b32_e32 v2, 3, v0
	v_lshl_or_b32 v1, v1, 6, v3
	v_lshlrev_b32_e32 v3, 2, v8
	v_cmp_eq_u32_e64 s[4:5], 0, v0
	v_lshlrev_b32_e32 v0, 14, v13
	v_and_b32_e32 v3, 32, v3
	v_and_b32_e32 v0, 0xffff8000, v0
	v_bitop3_b32 v4, v1, s16, v3 bitop3:0xde
	v_bitop3_b32 v149, s17, v1, v3 bitop3:0xf6
	v_lshl_add_u32 v0, v12, 11, v0
	v_and_b32_e32 v1, 1, v13
	v_lshl_or_b32 v0, v1, 6, v0
	v_lshl_add_u32 v136, v14, 1, v0
	v_lshlrev_b32_e32 v0, 14, v9
	v_and_b32_e32 v0, 0xffff8000, v0
	s_waitcnt vmcnt(6)
	v_lshl_add_u32 v0, v10, 11, v0
	v_and_b32_e32 v1, 1, v9
	v_lshl_or_b32 v0, v1, 6, v0
	s_add_i32 s53, 0, 0x10000
	s_add_i32 s54, 0, 0x14000
	v_lshl_or_b32 v150, s49, 5, v2
	s_ashr_i32 s52, s36, 31
	v_mov_b32_e32 v137, v133
	v_lshl_add_u32 v138, v11, 1, v0
	v_mov_b32_e32 v139, v133
	v_mov_b64_e32 v[140:141], 0x300
	v_mov_b64_e32 v[142:143], 0x2ff
	v_add_u32_e32 v151, s53, v149
	v_add_u32_e32 v152, 0, v4
	v_add_u32_e32 v153, s54, v149
	v_mbcnt_hi_u32_b32 v154, -1, v241
	s_mov_b32 s55, 0
	s_barrier
	s_branch .LBB0_783

.LBB0_889:
	s_lshl_b32 s6, s6, 5
	s_and_b32 s13, s6, 0x60
	s_lshl_b32 s12, s5, 13
	s_lshl_b32 s14, s13, 7
	s_add_u32 s6, s45, 0x9800000
	s_mov_b64 s[8:9], 0x80
	s_addc_u32 s7, s46, 0
	s_add_i32 m0, s19, 0x18000
	v_lshl_add_u64 v[6:7], v[6:7], 0, s[8:9]
	s_nop 0
	s_barrier
	global_load_lds_dwordx4 v[6:7], off
	v_lshl_add_u64 v[4:5], v[4:5], 0, s[8:9]
	s_add_i32 m0, s19, 0x1a000
	s_add_i32 s45, s19, 0x8000
	s_add_i32 s46, s19, 0xa000
	global_load_lds_dwordx4 v[4:5], off
	v_lshl_add_u64 v[2:3], v[2:3], 0, s[8:9]
	s_mov_b32 m0, s45
	s_add_u32 s10, s26, 0x40080
	global_load_lds_dwordx4 v[2:3], off
	v_lshl_add_u64 v[0:1], v[0:1], 0, s[8:9]
	s_mov_b32 m0, s46
	s_addc_u32 s11, s27, 0
	global_load_lds_dwordx4 v[0:1], off
	s_add_i32 m0, s19, 0x1c000
	v_lshl_add_u64 v[0:1], s[10:11], 0, v[132:133]
	global_load_lds_dwordx4 v[0:1], off
	v_lshl_add_u64 v[0:1], s[10:11], 0, v[128:129]
	s_add_i32 m0, s19, 0x1e000
	s_sext_i32_i16 s52, s4
	global_load_lds_dwordx4 v[0:1], off
	v_lshrrev_b32_e32 v1, 1, v145
	v_and_b32_e32 v1, 24, v1
	s_lshl_b32 s4, s5, 8
	v_and_b32_e32 v0, 15, v145
	v_lshlrev_b32_e32 v2, 1, v1
	s_add_i32 s4, s4, 0
	v_lshl_or_b32 v144, s5, 6, v0
	v_lshl_or_b32 v2, v0, 6, v2
	v_lshlrev_b32_e32 v0, 2, v0
	s_add_i32 s4, s4, 0x20000
	v_and_b32_e32 v3, 32, v0
	v_add_u32_e32 v146, s4, v0
	v_lshlrev_b32_e32 v0, 14, v12
	v_and_b32_e32 v0, 0xffff8000, v0
	v_or_b32_e32 v147, s13, v1
	v_lshl_add_u32 v0, v11, 11, v0
	v_and_b32_e32 v1, 1, v12
	v_lshl_or_b32 v0, v1, 6, v0
	v_lshl_add_u32 v136, v13, 1, v0
	v_lshlrev_b32_e32 v0, 14, v8
	v_and_b32_e32 v0, 0xffff8000, v0
	s_waitcnt vmcnt(6)
	v_lshl_add_u32 v0, v9, 11, v0
	v_and_b32_e32 v1, 1, v8
	v_bitop3_b32 v4, v2, s12, v3 bitop3:0xde
	v_bitop3_b32 v145, s14, v2, v3 bitop3:0xf6
	v_lshl_or_b32 v0, v1, 6, v0
	s_add_i32 s47, 0, 0x10000
	s_add_i32 s48, 0, 0x14000
	v_mov_b32_e32 v137, v133
	v_lshl_add_u32 v138, v10, 1, v0
	v_mov_b32_e32 v139, v133
	v_mov_b64_e32 v[140:141], 0x1080
	v_mov_b64_e32 v[142:143], 0x107f
	v_add_u32_e32 v148, s47, v145
	v_add_u32_e32 v149, 0, v4
	v_add_u32_e32 v150, s48, v145
	s_movk_i32 s49, 0x1600
	s_barrier

.LBB0_964:
	s_add_u32 s12, s4, 0x3800000
	s_addc_u32 s13, s5, 0
	s_add_u32 s14, s4, 0x3300000
	s_addc_u32 s15, s5, 0
	s_add_u32 s16, s4, 0x3798b00
	s_mov_b64 s[18:19], 0x80
	s_addc_u32 s17, s5, 0
	s_and_b32 s41, s3, 3
	s_add_i32 m0, s37, 0x18000
	v_lshl_add_u64 v[6:7], v[6:7], 0, s[18:19]
	s_lshl_b32 s3, s6, 13
	s_lshl_b32 s4, s41, 12
	s_nop 0
	s_barrier
	global_load_lds_dwordx4 v[6:7], off
	v_lshl_add_u64 v[4:5], v[4:5], 0, s[18:19]
	s_add_i32 m0, s37, 0x1a000
	s_add_i32 s42, s37, 0x8000
	s_add_i32 s43, s37, 0xa000
	global_load_lds_dwordx4 v[4:5], off
	v_lshl_add_u64 v[2:3], v[2:3], 0, s[18:19]
	s_mov_b32 m0, s42
	s_add_u32 s0, s22, 0xb0080
	global_load_lds_dwordx4 v[2:3], off
	v_lshl_add_u64 v[0:1], v[0:1], 0, s[18:19]
	s_mov_b32 m0, s43
	s_addc_u32 s1, s23, 0
	global_load_lds_dwordx4 v[0:1], off
	s_add_i32 m0, s37, 0x1c000
	v_lshl_add_u64 v[0:1], s[0:1], 0, v[130:131]
	global_load_lds_dwordx4 v[0:1], off
	v_lshl_add_u64 v[0:1], s[0:1], 0, v[134:135]
	s_add_i32 m0, s37, 0x1e000
	v_bfe_u32 v2, v240, 4, 2
	global_load_lds_dwordx4 v[0:1], off
	v_and_b32_e32 v1, 15, v240
	v_lshlrev_b32_e32 v0, 4, v2
	v_lshlrev_b32_e32 v4, 2, v240
	v_lshl_or_b32 v200, s6, 6, v1
	v_lshl_or_b32 v1, v1, 6, v0
	v_and_b32_e32 v4, 32, v4
	v_bitop3_b32 v5, v1, s3, v4 bitop3:0xde
	v_bitop3_b32 v201, s4, v1, v4 bitop3:0xf6
	v_mov_b32_e32 v1, v131
	v_lshl_add_u64 v[136:137], s[14:15], 0, v[0:1]
	v_lshrrev_b32_e32 v1, 1, v8
	v_mul_lo_u32 v0, v10, s2
	s_mov_b32 s3, 0xb000
	v_mad_u64_u32 v[0:1], s[6:7], v1, s3, v[0:1]
	v_or_b32_e32 v0, v0, v9
	s_mov_b64 s[4:5], 0xb0080
	v_add_lshl_u32 v0, v0, v11, 1
	v_mov_b32_e32 v1, v131
	v_lshl_add_u64 v[138:139], v[0:1], 0, s[4:5]
	v_lshrrev_b32_e32 v1, 1, v12
	v_mul_lo_u32 v0, v13, s2
	v_mad_u64_u32 v[0:1], s[2:3], v1, s3, v[0:1]
	s_waitcnt vmcnt(6)
	v_or_b32_e32 v0, v0, v14
	v_lshlrev_b32_e32 v3, 3, v2
	v_add_lshl_u32 v0, v0, v15, 1
	v_mov_b32_e32 v1, v131
	s_add_i32 s47, 0, 0x10000
	s_add_i32 s48, 0, 0x14000
	v_lshl_or_b32 v202, s41, 5, v3
	v_cmp_eq_u32_e64 s[0:1], 0, v2
	s_ashr_i32 s44, s29, 31
	s_ashr_i32 s45, s28, 31
	v_lshl_add_u64 v[140:141], v[0:1], 0, s[4:5]
	v_mov_b64_e32 v[142:143], 0x300
	v_mov_b64_e32 v[144:145], 0x2ff
	s_movk_i32 s46, 0x61
	v_add_u32_e32 v203, s47, v201
	v_add_u32_e32 v204, 0, v5
	v_add_u32_e32 v205, s48, v201
	v_mbcnt_hi_u32_b32 v206, -1, v241
	v_mov_b32_e32 v207, 0x358637bd
	s_mov_b32 s49, 0x800000
	s_mov_b32 s50, 0
	s_barrier
	s_branch .LBB0_966
